# v13 + branch-B K/V LDS-DMA addressing via SGPR base (vcc) + 32-bit VGPR offset
# baseline (speedup 1.0000x reference)
; #define SBAR() __builtin_amdgcn_sched_barrier(0)
; #define PIN(x) asm volatile("" : "+v"(x))
; template <int DK, bool NOMAX> ...
;     ...
;   float psa = 0.f, psb = 0.f;
;   SBAR();
; #pragma unroll
;   for (int d0 = 0; d0 < NS; ++d0) {
;     if (d0 == 0) { c0 = __builtin_amdgcn_mfma_f32_32x32x16_bf16(kf[0][0], qr[0], f32x16{}, 0, 0, 0); c1 = __builtin_amdgcn_mfma_f32_32x32x16_bf16(kf[0][1], qr[0], f32x16{}, 0, 0, 0); }
;     else { c0 = __builtin_amdgcn_mfma_f32_32x32x16_bf16(kf[d0 & 1][0], qr[d0], c0, 0, 0, 0); c1 = __builtin_amdgcn_mfma_f32_32x32x16_bf16(kf[d0 & 1][1], qr[d0], c1, 0, 0, 0); }
;     if (d0 + 2 < NS) KRD_(d0 & 1, d0 + 2);
;     if constexpr (NOMAX) { }
;     else {
; #pragma unroll
;     for (int r = d0 * RPS; r < (d0 + 1) * RPS; ++r) { p1[r] = __builtin_amdgcn_exp2f(p1[r]); psa += p0[r]; }
;     if (d0 > 0) {
; #pragma unroll
;       for (int r = (d0 - 1) * RPS; r < d0 * RPS; ++r) psb += p1[r]; } }
;     if constexpr (NOMAX) {
;       if (d0 == NS / 4 - 1) { PK4R(p0, 0, pa[0]); PIN(pa[0]); }
;       if (d0 == NS / 2 - 1) { PK4R(p0, 8, pa[1]); PIN(pa[1]); }
;       if (d0 == 3 * NS / 4 - 1) { PK4R(p1, 0, pa[2]); PIN(pa[2]); }
;       if (d0 == NS - 1) { PK4R(p1, 8, pa[3]); PIN(pa[3]); }
;     } else {
;     if (d0 == NS / 2 - 1) { PK4R(p0, 0, pa[0]); PIN(pa[0]); }
;     if (d0 == NS / 2) { PK4R(p0, 8, pa[1]); PIN(pa[1]); }
;     if (d0 == NS - 1) { PK4R(p1, 0, pa[2]); PIN(pa[2]); }
;     }
;     if (d0 == NS - 1) {
;       vl[0] = vtr(vp + v_rd_off(0, 0, 0)); vh[0] = vtr(vp + v_rd_off(0, 0, 1)); vl[1] = vtr(vp + v_rd_off(1, 0, 0)); vh[1] = vtr(vp + v_rd_off(1, 0, 1)); }
;     PIN(p1); PIN(psa); PIN(psb);
;     SBAR();
;   }
; template <int DK, bool NOMAX> ...
;     ...
; #pragma unroll
;   for (int i = 0; i < 16; ++i) {
;     if (i + 2 < 16) VRD_((i + 2) % 3, i + 2);
;     if (i == 1) { if (dk) __builtin_amdgcn_global_load_lds((const unsigned*)gk0, lk, 16, 0, 0); }
;     if (i == 3) { if constexpr (DK == 128) { if (dk) __builtin_amdgcn_global_load_lds((const unsigned*)gk1, (lds_up)((lds_cp)lk + 8192), 16, 0, 0); } }
;     if (i == 5) { if (dv) __builtin_amdgcn_global_load_lds((const unsigned*)gv0, lv, 16, 0, 0); }
;     if (i == 7) { if (dv) __builtin_amdgcn_global_load_lds((const unsigned*)gv1, (lds_up)((lds_cp)lv + 8192), 16, 0, 0); }
;     if (i == 12 || i == 13) { const int cb_ = ((i - 12) * 16 + hi * 8) * 2;
.LBB0_402:
	s_mov_b32 s17, s14
	s_mov_b32 s14, s8
	s_add_i32 s8, s18, 0xffffc000
	s_and_b32 s38, s8, 0xc000
	s_add_i32 s8, s38, 0
	v_add_u32_e32 v0, s14, v204
	s_waitcnt lgkmcnt(0)
	v_mfma_f32_32x32x16_bf16 v[114:129], v[102:105], v[158:161], 0
	v_add_u32_e32 v188, s8, v218
	ds_read_b128 v[184:187], v188
	ds_read_b128 v[188:191], v188 offset:8192
	v_mfma_f32_32x32x16_bf16 v[98:113], v[98:101], v[158:161], 0
	v_mfma_f32_32x32x16_bf16 v[114:129], v[166:169], v[154:157], v[114:129]
	v_mfma_f32_32x32x16_bf16 v[98:113], v[162:165], v[154:157], v[98:113]
	v_add_u32_e32 v162, s8, v219
	ds_read_b128 v[166:169], v162
	ds_read_b128 v[226:229], v162 offset:8192
	v_cvt_pk_bf16_f32 v162, v82, v83
	v_cvt_pk_bf16_f32 v163, v84, v85
	v_cvt_pk_bf16_f32 v164, v86, v87
	v_cvt_pk_bf16_f32 v165, v88, v89
	s_nop 0
	v_permlane32_swap_b32_e32 v162, v164
	v_permlane32_swap_b32_e32 v163, v165
	s_waitcnt lgkmcnt(3)
	v_mfma_f32_32x32x16_bf16 v[114:129], v[184:187], v[150:153], v[114:129]
	v_add_u32_e32 v86, s8, v220
	ds_read_b128 v[82:85], v86
	ds_read_b128 v[86:89], v86 offset:8192
	s_waitcnt lgkmcnt(4)
	v_mfma_f32_32x32x16_bf16 v[98:113], v[188:191], v[150:153], v[98:113]
	s_waitcnt lgkmcnt(3)
	v_mfma_f32_32x32x16_bf16 v[114:129], v[166:169], v[146:149], v[114:129]
	v_add_u32_e32 v184, s8, v221
	ds_read_b128 v[166:169], v184
	ds_read_b128 v[184:187], v184 offset:8192
	v_cvt_pk_bf16_f32 v90, v90, v91
	v_cvt_pk_bf16_f32 v91, v92, v93
	v_cvt_pk_bf16_f32 v92, v94, v95
	v_cvt_pk_bf16_f32 v93, v96, v97
	s_waitcnt lgkmcnt(4)
	v_mfma_f32_32x32x16_bf16 v[98:113], v[226:229], v[146:149], v[98:113]
	v_permlane32_swap_b32_e32 v90, v92
	v_permlane32_swap_b32_e32 v91, v93
	s_waitcnt lgkmcnt(3)
	v_mfma_f32_32x32x16_bf16 v[114:129], v[82:85], v[142:145], v[114:129]
	s_waitcnt lgkmcnt(2)
	v_mfma_f32_32x32x16_bf16 v[98:113], v[86:89], v[142:145], v[98:113]
	v_add_u32_e32 v86, s8, v222
	ds_read_b128 v[82:85], v86
	ds_read_b128 v[94:97], v86 offset:8192
	s_waitcnt lgkmcnt(3)
	v_mfma_f32_32x32x16_bf16 v[114:129], v[166:169], v[138:141], v[114:129]
	v_add_u32_e32 v86, s8, v223
	s_waitcnt lgkmcnt(2)
	v_mfma_f32_32x32x16_bf16 v[98:113], v[184:187], v[138:141], v[98:113]
	ds_read_b128 v[166:169], v86
	ds_read_b128 v[184:187], v86 offset:8192
	v_cvt_pk_bf16_f32 v86, v66, v67
	v_cvt_pk_bf16_f32 v87, v68, v69
	v_cvt_pk_bf16_f32 v88, v70, v71
	v_cvt_pk_bf16_f32 v89, v72, v73
	s_nop 0
	v_permlane32_swap_b32_e32 v86, v88
	v_permlane32_swap_b32_e32 v87, v89
	s_waitcnt lgkmcnt(3)
	v_mfma_f32_32x32x16_bf16 v[114:129], v[82:85], v[130:133], v[114:129]
	s_waitcnt lgkmcnt(2)
	v_mfma_f32_32x32x16_bf16 v[98:113], v[94:97], v[130:133], v[98:113]
	v_cvt_pk_bf16_f32 v82, v74, v75
	v_cvt_pk_bf16_f32 v83, v76, v77
	v_cvt_pk_bf16_f32 v84, v78, v79
	v_cvt_pk_bf16_f32 v85, v80, v81
	s_waitcnt lgkmcnt(1)
	v_mfma_f32_32x32x16_bf16 v[114:129], v[166:169], v[134:137], v[114:129]
	v_permlane32_swap_b32_e32 v82, v84
	v_permlane32_swap_b32_e32 v83, v85
	ds_read_b64_tr_b16 v[166:167], v0
	ds_read_b64_tr_b16 v[168:169], v0 offset:2048
	ds_read_b64_tr_b16 v[94:95], v0 offset:512
	ds_read_b64_tr_b16 v[96:97], v0 offset:2560
	s_waitcnt lgkmcnt(4)
	v_mfma_f32_32x32x16_bf16 v[98:113], v[184:187], v[134:137], v[98:113]
	s_cmpk_lt_u32 s15, 0x7d
	s_cselect_b64 s[10:11], -1, 0
	s_cmpk_gt_u32 s15, 0x7c
	s_cselect_b64 s[8:9], -1, 0
	s_add_i32 s19, s18, 0x8000
	s_and_b32 s12, s19, 0xc000
	ds_read_b64_tr_b16 v[70:71], v0 offset:1024
	ds_read_b64_tr_b16 v[72:73], v0 offset:3072
	s_waitcnt lgkmcnt(4)
	v_mfma_f32_32x32x16_bf16 v[50:65], v[162:165], v[166:169], v[50:65]
	v_exp_f32_e32 v114, v114
	s_nop 0
	v_exp_f32_e32 v98, v98
	ds_read_b64_tr_b16 v[66:67], v0 offset:1536
	ds_read_b64_tr_b16 v[68:69], v0 offset:3584
	s_and_b64 vcc, exec, s[8:9]
	s_cbranch_vccnz .LBB0_404
	s_add_u32 vcc_lo, s0, s50
	s_addc_u32 vcc_hi, s1, s51
	s_add_i32 m0, s2, s12
	s_nop 0
	global_load_lds_dwordx4 v182, vcc
.LBB0_404:
	s_waitcnt lgkmcnt(4)
	v_mfma_f32_32x32x16_bf16 v[34:49], v[162:165], v[94:97], v[34:49]
	v_exp_f32_e32 v115, v115
	v_exp_f32_e32 v99, v99
	ds_read_b64_tr_b16 v[74:75], v0 offset:4096
	ds_read_b64_tr_b16 v[76:77], v0 offset:6144
	s_waitcnt lgkmcnt(4)
	v_mfma_f32_32x32x16_bf16 v[18:33], v[162:165], v[70:73], v[18:33]
	v_exp_f32_e32 v116, v116
	v_exp_f32_e32 v100, v100
	v_add_f32_e32 v79, v99, v98
	v_add_f32_e32 v78, v115, v114
	ds_read_b64_tr_b16 v[70:71], v0 offset:4608
	ds_read_b64_tr_b16 v[72:73], v0 offset:6656
	s_andn2_b64 vcc, exec, s[10:11]
	s_cbranch_vccnz .LBB0_406
	s_add_i32 s10, s2, s12
	s_add_u32 vcc_lo, s0, s50
	s_addc_u32 vcc_hi, s1, s51
	s_add_i32 m0, s10, 0x2000
	s_nop 0
	global_load_lds_dwordx4 v180, vcc
; template <int DK, bool NOMAX> ...
;     ...
; #pragma unroll
;   for (int i = 0; i < 16; ++i) {
;     if (i + 2 < 16) VRD_((i + 2) % 3, i + 2);
;     if (i == 1) { if (dk) __builtin_amdgcn_global_load_lds((const unsigned*)gk0, lk, 16, 0, 0); }
;     if (i == 3) { if constexpr (DK == 128) { if (dk) __builtin_amdgcn_global_load_lds((const unsigned*)gk1, (lds_up)((lds_cp)lk + 8192), 16, 0, 0); } }
;     if (i == 5) { if (dv) __builtin_amdgcn_global_load_lds((const unsigned*)gv0, lv, 16, 0, 0); }
;     if (i == 7) { if (dv) __builtin_amdgcn_global_load_lds((const unsigned*)gv1, (lds_up)((lds_cp)lv + 8192), 16, 0, 0); }
;     if (i == 12 || i == 13) { const int cb_ = ((i - 12) * 16 + hi * 8) * 2;
;       if constexpr (DK == 128) { kf[i - 12][0] = *reinterpret_cast<const bf16x8*>(Kn + KSWZ128(r32, cb_)); kf[i - 12][1] = *reinterpret_cast<const bf16x8*>(Kn + KSWZ128(32 + r32, cb_)); }
;       else { kf[i - 12][0] = *reinterpret_cast<const bf16x8*>(Kn + KSWZ64(r32, cb_)); kf[i - 12][1] = *reinterpret_cast<const bf16x8*>(Kn + KSWZ64(32 + r32, cb_)); } }
;     SBAR();
;     o[i & 3] = __builtin_amdgcn_mfma_f32_32x32x16_bf16(pa[i >> 2], VFR_(i % 3), o[i & 3], 0, 0, 0);
;     if constexpr (NOMAX) { c0[i] = __builtin_amdgcn_exp2f(c0[i]); c1[i] = __builtin_amdgcn_exp2f(c1[i]); if (i > 0) { psa += c0[i - 1]; psb += c1[i - 1]; } PIN(c0); PIN(c1); PIN(psa); PIN(psb); }
;     else {
;     if (i == 0) { ma = max3f(c0[0], c0[1], c1[0]); mb = max3f(c0[2], c0[3], c1[1]); ma = max3f(ma, c1[2], c1[3]); }
;     if (i >= 1 && i <= 3) { const int r = 4 * i; ma = max3f(ma, c0[r], c0[r + 1]); mb = max3f(mb, c0[r + 2], c0[r + 3]); ma = max3f(ma, c1[r], c1[r + 1]); mb = max3f(mb, c1[r + 2], c1[r + 3]); }
;     if (i == 4) { float pmax = fmaxf(ma, mb);
;       { auto rr = __builtin_amdgcn_permlane32_swap(__float_as_uint(pmax), __float_as_uint(pmax), false, false);
;         pmax = fmaxf(__uint_as_float(rr[0]), __uint_as_float(rr[1])); }
;       pmax += cb;
;       const bool keep = __all(pmax - m_reg <= THR2);
;       const float mn = keep ? m_reg : fmaxf(m_reg, pmax);
;       alpha = __builtin_amdgcn_exp2f(m_reg - mn); m_reg = mn; mnC = cb - mn; }
;     if (i >= 5 && i <= 8) { const int r = 4 * (i - 5);
; #pragma unroll
;       for (int q = 0; q < 4; ++q) { c0[r + q] += mnC; c1[r + q] += mnC; } }
;     if (i >= 9) { const int r0 = (i - 9) * 2 + (i > 14 ? 1 : 0), n = i >= 14 ? 3 : 2;
.LBB0_406:
	s_and_b32 s10, s18, 0xc000
	s_add_i32 s12, s10, 0
	s_waitcnt lgkmcnt(4)
	v_mfma_f32_32x32x16_bf16 v[2:17], v[162:165], v[66:69], v[2:17]
	v_exp_f32_e32 v117, v117
	v_exp_f32_e32 v101, v101
	v_add_f32_e32 v79, v100, v79
	v_add_f32_e32 v78, v116, v78
	ds_read_b64_tr_b16 v[66:67], v0 offset:5120
	ds_read_b64_tr_b16 v[68:69], v0 offset:7168
	s_waitcnt lgkmcnt(4)
	v_mfma_f32_32x32x16_bf16 v[50:65], v[90:93], v[74:77], v[50:65]
	v_exp_f32_e32 v118, v118
	v_exp_f32_e32 v102, v102
	v_add_f32_e32 v79, v101, v79
	v_add_f32_e32 v78, v117, v78
	s_add_u32 vcc_lo, s0, s60
	s_addc_u32 vcc_hi, s1, s61
	s_add_i32 s10, s3, s16
	s_mov_b32 m0, s10
	ds_read_b64_tr_b16 v[74:75], v0 offset:5632
	ds_read_b64_tr_b16 v[76:77], v0 offset:7680
	global_load_lds_dwordx4 v172, vcc
	s_waitcnt lgkmcnt(4)
	v_mfma_f32_32x32x16_bf16 v[34:49], v[90:93], v[70:73], v[34:49]
	v_exp_f32_e32 v119, v119
	v_exp_f32_e32 v103, v103
	v_add_f32_e32 v79, v102, v79
	v_add_f32_e32 v78, v118, v78
	ds_read_b64_tr_b16 v[70:71], v0 offset:8192
	ds_read_b64_tr_b16 v[72:73], v0 offset:10240
	s_waitcnt lgkmcnt(4)
	v_mfma_f32_32x32x16_bf16 v[18:33], v[90:93], v[66:69], v[18:33]
	v_exp_f32_e32 v120, v120
	v_exp_f32_e32 v104, v104
	v_add_f32_e32 v79, v103, v79
	v_add_f32_e32 v78, v119, v78
	s_add_i32 m0, s10, 0x2000
	ds_read_b64_tr_b16 v[66:67], v0 offset:8704
	ds_read_b64_tr_b16 v[68:69], v0 offset:10752
	global_load_lds_dwordx4 v170, vcc
	s_waitcnt lgkmcnt(4)
	v_mfma_f32_32x32x16_bf16 v[2:17], v[90:93], v[74:77], v[2:17]
	v_exp_f32_e32 v121, v121
	v_exp_f32_e32 v105, v105
	v_add_f32_e32 v79, v104, v79
	v_add_f32_e32 v78, v120, v78
	ds_read_b64_tr_b16 v[74:75], v0 offset:9216
	ds_read_b64_tr_b16 v[76:77], v0 offset:11264
	s_waitcnt lgkmcnt(4)
	v_mfma_f32_32x32x16_bf16 v[50:65], v[86:89], v[70:73], v[50:65]
	v_exp_f32_e32 v122, v122
	v_exp_f32_e32 v106, v106
	v_add_f32_e32 v79, v105, v79
	v_add_f32_e32 v78, v121, v78
	ds_read_b64_tr_b16 v[70:71], v0 offset:9728
	ds_read_b64_tr_b16 v[72:73], v0 offset:11776
	s_waitcnt lgkmcnt(4)
	v_mfma_f32_32x32x16_bf16 v[34:49], v[86:89], v[66:69], v[34:49]
	v_exp_f32_e32 v123, v123
	v_exp_f32_e32 v107, v107
	v_add_f32_e32 v66, v106, v79
	v_add_f32_e32 v67, v122, v78
	ds_read_b64_tr_b16 v[78:79], v0 offset:12288
	ds_read_b64_tr_b16 v[80:81], v0 offset:14336
	s_waitcnt lgkmcnt(4)
	v_mfma_f32_32x32x16_bf16 v[18:33], v[86:89], v[74:77], v[18:33]
	v_exp_f32_e32 v124, v124
	v_exp_f32_e32 v108, v108
	v_add_f32_e32 v66, v107, v66
	v_add_f32_e32 v67, v123, v67
	ds_read_b64_tr_b16 v[74:75], v0 offset:12800
	ds_read_b64_tr_b16 v[76:77], v0 offset:14848
	s_waitcnt lgkmcnt(4)
	v_mfma_f32_32x32x16_bf16 v[2:17], v[86:89], v[70:73], v[2:17]
	v_exp_f32_e32 v125, v125
	v_exp_f32_e32 v109, v109
	v_add_f32_e32 v90, v108, v66
	v_add_f32_e32 v91, v124, v67
	v_add_u32_e32 v70, s12, v224
	ds_read_b64_tr_b16 v[86:87], v0 offset:13312
	ds_read_b64_tr_b16 v[88:89], v0 offset:15360
	ds_read_b128 v[66:69], v70
	ds_read_b128 v[70:73], v70 offset:8192
	s_waitcnt lgkmcnt(6)
	v_mfma_f32_32x32x16_bf16 v[50:65], v[82:85], v[78:81], v[50:65]
	v_exp_f32_e32 v126, v126
	v_exp_f32_e32 v110, v110
	v_add_f32_e32 v90, v109, v90
	v_add_f32_e32 v91, v125, v91
	ds_read_b64_tr_b16 v[78:79], v0 offset:13824
	ds_read_b64_tr_b16 v[80:81], v0 offset:15872
	v_add_u32_e32 v0, s12, v225
	ds_read_b128 v[162:165], v0
	ds_read_b128 v[166:169], v0 offset:8192
	s_waitcnt lgkmcnt(8)
	v_mfma_f32_32x32x16_bf16 v[34:49], v[82:85], v[74:77], v[34:49]
	v_exp_f32_e32 v127, v127
	v_exp_f32_e32 v111, v111
	v_add_f32_e32 v0, v110, v90
	v_add_f32_e32 v74, v126, v91
	s_waitcnt lgkmcnt(6)
	v_mfma_f32_32x32x16_bf16 v[18:33], v[82:85], v[86:89], v[18:33]
	v_exp_f32_e32 v128, v128
	v_exp_f32_e32 v112, v112
	v_add_f32_e32 v0, v111, v0
	v_add_f32_e32 v74, v127, v74
	s_waitcnt lgkmcnt(2)
	v_mfma_f32_32x32x16_bf16 v[2:17], v[82:85], v[78:81], v[2:17]
	v_exp_f32_e32 v129, v129
	v_exp_f32_e32 v113, v113
	v_add_f32_e32 v0, v112, v0
	v_add_f32_e32 v74, v128, v74
	s_nop 0
	v_add_f32_e32 v74, v129, v74
	v_add_f32_e32 v0, v113, v0
	v_add_f32_e32 v0, v74, v0
	v_mov_b32_e32 v226, v0
	s_nop 1
	v_permlane32_swap_b32_e32 v0, v226
	s_mov_b64 s[10:11], -1
	s_and_b64 vcc, exec, s[8:9]
	s_cbranch_vccz .LBB0_408
	s_waitcnt vmcnt(0) lgkmcnt(0)
	s_barrier
	s_mov_b64 s[10:11], 0

; #define SBAR() __builtin_amdgcn_sched_barrier(0)
; #define PIN(x) asm volatile("" : "+v"(x))
; template <int DK, bool NOMAX> ...
;     ...
;   float psa = 0.f, psb = 0.f;
;   SBAR();
; #pragma unroll
;   for (int d0 = 0; d0 < NS; ++d0) {
;     if (d0 == 0) { c0 = __builtin_amdgcn_mfma_f32_32x32x16_bf16(kf[0][0], qr[0], f32x16{}, 0, 0, 0); c1 = __builtin_amdgcn_mfma_f32_32x32x16_bf16(kf[0][1], qr[0], f32x16{}, 0, 0, 0); }
;     else { c0 = __builtin_amdgcn_mfma_f32_32x32x16_bf16(kf[d0 & 1][0], qr[d0], c0, 0, 0, 0); c1 = __builtin_amdgcn_mfma_f32_32x32x16_bf16(kf[d0 & 1][1], qr[d0], c1, 0, 0, 0); }
;     if (d0 + 2 < NS) KRD_(d0 & 1, d0 + 2);
;     if constexpr (NOMAX) { }
;     else {
; #pragma unroll
;     for (int r = d0 * RPS; r < (d0 + 1) * RPS; ++r) { p1[r] = __builtin_amdgcn_exp2f(p1[r]); psa += p0[r]; }
;     if (d0 > 0) {
; #pragma unroll
;       for (int r = (d0 - 1) * RPS; r < d0 * RPS; ++r) psb += p1[r]; } }
;     if constexpr (NOMAX) {
;       if (d0 == NS / 4 - 1) { PK4R(p0, 0, pa[0]); PIN(pa[0]); }
;       if (d0 == NS / 2 - 1) { PK4R(p0, 8, pa[1]); PIN(pa[1]); }
;       if (d0 == 3 * NS / 4 - 1) { PK4R(p1, 0, pa[2]); PIN(pa[2]); }
;       if (d0 == NS - 1) { PK4R(p1, 8, pa[3]); PIN(pa[3]); }
;     } else {
;     if (d0 == NS / 2 - 1) { PK4R(p0, 0, pa[0]); PIN(pa[0]); }
;     if (d0 == NS / 2) { PK4R(p0, 8, pa[1]); PIN(pa[1]); }
;     if (d0 == NS - 1) { PK4R(p1, 0, pa[2]); PIN(pa[2]); }
;     }
;     if (d0 == NS - 1) {
;       vl[0] = vtr(vp + v_rd_off(0, 0, 0)); vh[0] = vtr(vp + v_rd_off(0, 0, 1)); vl[1] = vtr(vp + v_rd_off(1, 0, 0)); vh[1] = vtr(vp + v_rd_off(1, 0, 1)); }
;     PIN(p1); PIN(psa); PIN(psb);
;     SBAR();
;   }
; template <int DK, bool NOMAX> ...
;     ...
; #pragma unroll
;   for (int i = 0; i < 16; ++i) {
;     if (i + 2 < 16) VRD_((i + 2) % 3, i + 2);
;     if (i == 1) { if (dk) __builtin_amdgcn_global_load_lds((const unsigned*)gk0, lk, 16, 0, 0); }
;     if (i == 3) { if constexpr (DK == 128) { if (dk) __builtin_amdgcn_global_load_lds((const unsigned*)gk1, (lds_up)((lds_cp)lk + 8192), 16, 0, 0); } }
;     if (i == 5) { if (dv) __builtin_amdgcn_global_load_lds((const unsigned*)gv0, lv, 16, 0, 0); }
;     if (i == 7) { if (dv) __builtin_amdgcn_global_load_lds((const unsigned*)gv1, (lds_up)((lds_cp)lv + 8192), 16, 0, 0); }
;     if (i == 12 || i == 13) { const int cb_ = ((i - 12) * 16 + hi * 8) * 2;
.LBB0_410:
	v_add_u32_e32 v227, s17, v204
	v_mfma_f32_32x32x16_bf16 v[82:97], v[66:69], v[158:161], 0
	v_add_u32_e32 v232, s12, v218
	ds_read_b128 v[228:231], v232
	ds_read_b128 v[232:235], v232 offset:8192
	v_mfma_f32_32x32x16_bf16 v[66:81], v[70:73], v[158:161], 0
	v_mfma_f32_32x32x16_bf16 v[82:97], v[162:165], v[154:157], v[82:97]
	v_add_u32_e32 v162, s12, v219
	v_mfma_f32_32x32x16_bf16 v[66:81], v[166:169], v[154:157], v[66:81]
	ds_read_b128 v[166:169], v162
	ds_read_b128 v[236:239], v162 offset:8192
	v_cvt_pk_bf16_f32 v162, v114, v115
	v_cvt_pk_bf16_f32 v163, v116, v117
	v_cvt_pk_bf16_f32 v164, v118, v119
	v_cvt_pk_bf16_f32 v165, v120, v121
	s_nop 0
	v_permlane32_swap_b32_e32 v162, v164
	v_permlane32_swap_b32_e32 v163, v165
	s_waitcnt lgkmcnt(3)
	v_mfma_f32_32x32x16_bf16 v[82:97], v[228:231], v[150:153], v[82:97]
	v_add_u32_e32 v118, s12, v220
	ds_read_b128 v[114:117], v118
	ds_read_b128 v[118:121], v118 offset:8192
	s_waitcnt lgkmcnt(4)
	v_mfma_f32_32x32x16_bf16 v[66:81], v[232:235], v[150:153], v[66:81]
	s_waitcnt lgkmcnt(3)
	v_mfma_f32_32x32x16_bf16 v[82:97], v[166:169], v[146:149], v[82:97]
	v_add_u32_e32 v228, s12, v221
	ds_read_b128 v[166:169], v228
	ds_read_b128 v[228:231], v228 offset:8192
	v_cvt_pk_bf16_f32 v122, v122, v123
	v_cvt_pk_bf16_f32 v123, v124, v125
	v_cvt_pk_bf16_f32 v124, v126, v127
	v_cvt_pk_bf16_f32 v125, v128, v129
	s_waitcnt lgkmcnt(4)
	v_mfma_f32_32x32x16_bf16 v[66:81], v[236:239], v[146:149], v[66:81]
	v_permlane32_swap_b32_e32 v122, v124
	v_permlane32_swap_b32_e32 v123, v125
	s_waitcnt lgkmcnt(3)
	v_mfma_f32_32x32x16_bf16 v[82:97], v[114:117], v[142:145], v[82:97]
	s_waitcnt lgkmcnt(2)
	v_mfma_f32_32x32x16_bf16 v[66:81], v[118:121], v[142:145], v[66:81]
	v_add_u32_e32 v118, s12, v222
	ds_read_b128 v[114:117], v118
	ds_read_b128 v[126:129], v118 offset:8192
	s_waitcnt lgkmcnt(3)
	v_mfma_f32_32x32x16_bf16 v[82:97], v[166:169], v[138:141], v[82:97]
	v_add_u32_e32 v118, s12, v223
	s_waitcnt lgkmcnt(2)
	v_mfma_f32_32x32x16_bf16 v[66:81], v[228:231], v[138:141], v[66:81]
	ds_read_b128 v[166:169], v118
	ds_read_b128 v[228:231], v118 offset:8192
	v_cvt_pk_bf16_f32 v118, v98, v99
	v_cvt_pk_bf16_f32 v119, v100, v101
	v_cvt_pk_bf16_f32 v120, v102, v103
	v_cvt_pk_bf16_f32 v121, v104, v105
	s_nop 0
	v_permlane32_swap_b32_e32 v118, v120
	v_permlane32_swap_b32_e32 v119, v121
	s_waitcnt lgkmcnt(3)
	v_mfma_f32_32x32x16_bf16 v[82:97], v[114:117], v[130:133], v[82:97]
	s_waitcnt lgkmcnt(2)
	v_mfma_f32_32x32x16_bf16 v[66:81], v[126:129], v[130:133], v[66:81]
	v_cvt_pk_bf16_f32 v114, v106, v107
	v_cvt_pk_bf16_f32 v115, v108, v109
	v_cvt_pk_bf16_f32 v116, v110, v111
	v_cvt_pk_bf16_f32 v117, v112, v113
	s_waitcnt lgkmcnt(1)
	v_mfma_f32_32x32x16_bf16 v[82:97], v[166:169], v[134:137], v[82:97]
	v_permlane32_swap_b32_e32 v114, v116
	v_permlane32_swap_b32_e32 v115, v117
	ds_read_b64_tr_b16 v[166:167], v227
	ds_read_b64_tr_b16 v[168:169], v227 offset:2048
	ds_read_b64_tr_b16 v[126:127], v227 offset:512
	ds_read_b64_tr_b16 v[128:129], v227 offset:2560
	s_waitcnt lgkmcnt(4)
	v_mfma_f32_32x32x16_bf16 v[66:81], v[228:231], v[134:137], v[66:81]
	s_cmpk_lt_u32 s15, 0x7c
	s_cselect_b64 s[12:13], -1, 0
	s_cmpk_gt_u32 s15, 0x7b
	s_cselect_b64 s[10:11], -1, 0
	ds_read_b64_tr_b16 v[102:103], v227 offset:1024
	ds_read_b64_tr_b16 v[104:105], v227 offset:3072
	s_waitcnt lgkmcnt(4)
	v_mfma_f32_32x32x16_bf16 v[50:65], v[162:165], v[166:169], v[50:65]
	v_exp_f32_e32 v82, v82
	s_nop 2
	v_exp_f32_e32 v66, v66
	ds_read_b64_tr_b16 v[98:99], v227 offset:1536
	ds_read_b64_tr_b16 v[100:101], v227 offset:3584
	s_and_b64 vcc, exec, s[10:11]
	s_cbranch_vccnz .LBB0_412
	s_add_u32 vcc_lo, s0, s64
	s_addc_u32 vcc_hi, s1, s65
	s_add_i32 m0, s2, s38
	s_nop 0
	global_load_lds_dwordx4 v182, vcc
.LBB0_412:
	s_waitcnt lgkmcnt(4)
	v_mfma_f32_32x32x16_bf16 v[34:49], v[162:165], v[126:129], v[34:49]
	v_exp_f32_e32 v83, v83
	v_exp_f32_e32 v67, v67
	ds_read_b64_tr_b16 v[106:107], v227 offset:4096
	ds_read_b64_tr_b16 v[108:109], v227 offset:6144
	s_waitcnt lgkmcnt(4)
	v_mfma_f32_32x32x16_bf16 v[18:33], v[162:165], v[102:105], v[18:33]
	v_exp_f32_e32 v84, v84
	v_exp_f32_e32 v68, v68
	v_add_f32_e32 v111, v67, v66
	v_add_f32_e32 v110, v83, v82
	ds_read_b64_tr_b16 v[102:103], v227 offset:4608
	ds_read_b64_tr_b16 v[104:105], v227 offset:6656
	s_andn2_b64 vcc, exec, s[12:13]
	s_cbranch_vccnz .LBB0_414
	s_add_i32 s12, s2, s38
	s_add_u32 vcc_lo, s0, s64
	s_addc_u32 vcc_hi, s1, s65
	s_add_i32 m0, s12, 0x2000
	s_nop 0
	global_load_lds_dwordx4 v180, vcc
; template <int DK, bool NOMAX> ...
;     ...
; #pragma unroll
;   for (int i = 0; i < 16; ++i) {
;     if (i + 2 < 16) VRD_((i + 2) % 3, i + 2);
;     if (i == 1) { if (dk) __builtin_amdgcn_global_load_lds((const unsigned*)gk0, lk, 16, 0, 0); }
;     if (i == 3) { if constexpr (DK == 128) { if (dk) __builtin_amdgcn_global_load_lds((const unsigned*)gk1, (lds_up)((lds_cp)lk + 8192), 16, 0, 0); } }
;     if (i == 5) { if (dv) __builtin_amdgcn_global_load_lds((const unsigned*)gv0, lv, 16, 0, 0); }
;     if (i == 7) { if (dv) __builtin_amdgcn_global_load_lds((const unsigned*)gv1, (lds_up)((lds_cp)lv + 8192), 16, 0, 0); }
;     if (i == 12 || i == 13) { const int cb_ = ((i - 12) * 16 + hi * 8) * 2;
;       if constexpr (DK == 128) { kf[i - 12][0] = *reinterpret_cast<const bf16x8*>(Kn + KSWZ128(r32, cb_)); kf[i - 12][1] = *reinterpret_cast<const bf16x8*>(Kn + KSWZ128(32 + r32, cb_)); }
;       else { kf[i - 12][0] = *reinterpret_cast<const bf16x8*>(Kn + KSWZ64(r32, cb_)); kf[i - 12][1] = *reinterpret_cast<const bf16x8*>(Kn + KSWZ64(32 + r32, cb_)); } }
;     SBAR();
;     o[i & 3] = __builtin_amdgcn_mfma_f32_32x32x16_bf16(pa[i >> 2], VFR_(i % 3), o[i & 3], 0, 0, 0);
;     if constexpr (NOMAX) { c0[i] = __builtin_amdgcn_exp2f(c0[i]); c1[i] = __builtin_amdgcn_exp2f(c1[i]); if (i > 0) { psa += c0[i - 1]; psb += c1[i - 1]; } PIN(c0); PIN(c1); PIN(psa); PIN(psb); }
;     else {
;     if (i == 0) { ma = max3f(c0[0], c0[1], c1[0]); mb = max3f(c0[2], c0[3], c1[1]); ma = max3f(ma, c1[2], c1[3]); }
;     if (i >= 1 && i <= 3) { const int r = 4 * i; ma = max3f(ma, c0[r], c0[r + 1]); mb = max3f(mb, c0[r + 2], c0[r + 3]); ma = max3f(ma, c1[r], c1[r + 1]); mb = max3f(mb, c1[r + 2], c1[r + 3]); }
;     if (i == 4) { float pmax = fmaxf(ma, mb);
;       { auto rr = __builtin_amdgcn_permlane32_swap(__float_as_uint(pmax), __float_as_uint(pmax), false, false);
;         pmax = fmaxf(__uint_as_float(rr[0]), __uint_as_float(rr[1])); }
;       pmax += cb;
;       const bool keep = __all(pmax - m_reg <= THR2);
;       const float mn = keep ? m_reg : fmaxf(m_reg, pmax);
;       alpha = __builtin_amdgcn_exp2f(m_reg - mn); m_reg = mn; mnC = cb - mn; }
;     if (i >= 5 && i <= 8) { const int r = 4 * (i - 5);
; #pragma unroll
;       for (int q = 0; q < 4; ++q) { c0[r + q] += mnC; c1[r + q] += mnC; } }
;     if (i >= 9) { const int r0 = (i - 9) * 2 + (i > 14 ? 1 : 0), n = i >= 14 ? 3 : 2;
.LBB0_414:
	s_add_i32 s12, s18, 0x4000
	s_and_b32 s12, s12, 0xc000
	s_add_i32 s12, s12, 0
	s_waitcnt lgkmcnt(4)
	v_mfma_f32_32x32x16_bf16 v[2:17], v[162:165], v[98:101], v[2:17]
	v_exp_f32_e32 v85, v85
	v_exp_f32_e32 v69, v69
	v_add_f32_e32 v111, v68, v111
	v_add_f32_e32 v110, v84, v110
	ds_read_b64_tr_b16 v[98:99], v227 offset:5120
	ds_read_b64_tr_b16 v[100:101], v227 offset:7168
	s_waitcnt lgkmcnt(4)
	v_mfma_f32_32x32x16_bf16 v[50:65], v[122:125], v[106:109], v[50:65]
	v_exp_f32_e32 v86, v86
	v_exp_f32_e32 v70, v70
	v_add_f32_e32 v111, v69, v111
	v_add_f32_e32 v110, v85, v110
	s_add_u32 vcc_lo, s0, s24
	s_addc_u32 vcc_hi, s1, s25
	s_add_i32 s13, s3, s14
	s_mov_b32 m0, s13
	ds_read_b64_tr_b16 v[106:107], v227 offset:5632
	ds_read_b64_tr_b16 v[108:109], v227 offset:7680
	global_load_lds_dwordx4 v172, vcc
	s_waitcnt lgkmcnt(4)
	v_mfma_f32_32x32x16_bf16 v[34:49], v[122:125], v[102:105], v[34:49]
	v_exp_f32_e32 v87, v87
	v_exp_f32_e32 v71, v71
	v_add_f32_e32 v111, v70, v111
	v_add_f32_e32 v110, v86, v110
	ds_read_b64_tr_b16 v[102:103], v227 offset:8192
	ds_read_b64_tr_b16 v[104:105], v227 offset:10240
	s_waitcnt lgkmcnt(4)
	v_mfma_f32_32x32x16_bf16 v[18:33], v[122:125], v[98:101], v[18:33]
	v_exp_f32_e32 v88, v88
	v_exp_f32_e32 v72, v72
	v_add_f32_e32 v111, v71, v111
	v_add_f32_e32 v110, v87, v110
	s_add_i32 m0, s13, 0x2000
	ds_read_b64_tr_b16 v[98:99], v227 offset:8704
	ds_read_b64_tr_b16 v[100:101], v227 offset:10752
	global_load_lds_dwordx4 v170, vcc
	s_waitcnt lgkmcnt(4)
	v_mfma_f32_32x32x16_bf16 v[2:17], v[122:125], v[106:109], v[2:17]
	v_exp_f32_e32 v89, v89
	v_exp_f32_e32 v73, v73
	v_add_f32_e32 v111, v72, v111
	v_add_f32_e32 v110, v88, v110
	ds_read_b64_tr_b16 v[106:107], v227 offset:9216
	ds_read_b64_tr_b16 v[108:109], v227 offset:11264
	s_waitcnt lgkmcnt(4)
	v_mfma_f32_32x32x16_bf16 v[50:65], v[118:121], v[102:105], v[50:65]
	v_exp_f32_e32 v90, v90
	v_exp_f32_e32 v74, v74
	v_add_f32_e32 v111, v73, v111
	v_add_f32_e32 v110, v89, v110
	ds_read_b64_tr_b16 v[102:103], v227 offset:9728
	ds_read_b64_tr_b16 v[104:105], v227 offset:11776
	s_waitcnt lgkmcnt(4)
	v_mfma_f32_32x32x16_bf16 v[34:49], v[118:121], v[98:101], v[34:49]
	v_exp_f32_e32 v91, v91
	v_exp_f32_e32 v75, v75
	v_add_f32_e32 v98, v74, v111
	v_add_f32_e32 v99, v90, v110
	ds_read_b64_tr_b16 v[110:111], v227 offset:12288
	ds_read_b64_tr_b16 v[112:113], v227 offset:14336
	s_waitcnt lgkmcnt(4)
	v_mfma_f32_32x32x16_bf16 v[18:33], v[118:121], v[106:109], v[18:33]
	v_exp_f32_e32 v92, v92
	v_exp_f32_e32 v76, v76
	v_add_f32_e32 v98, v75, v98
	v_add_f32_e32 v99, v91, v99
	ds_read_b64_tr_b16 v[106:107], v227 offset:12800
	ds_read_b64_tr_b16 v[108:109], v227 offset:14848
	s_waitcnt lgkmcnt(4)
	v_mfma_f32_32x32x16_bf16 v[2:17], v[118:121], v[102:105], v[2:17]
	v_exp_f32_e32 v93, v93
	v_exp_f32_e32 v77, v77
	v_add_f32_e32 v122, v76, v98
	v_add_f32_e32 v123, v92, v99
	v_add_u32_e32 v98, s12, v224
	ds_read_b64_tr_b16 v[118:119], v227 offset:13312
	ds_read_b64_tr_b16 v[120:121], v227 offset:15360
	ds_read_b128 v[102:105], v98
	ds_read_b128 v[98:101], v98 offset:8192
	s_waitcnt lgkmcnt(6)
	v_mfma_f32_32x32x16_bf16 v[50:65], v[114:117], v[110:113], v[50:65]
	v_exp_f32_e32 v94, v94
	v_exp_f32_e32 v78, v78
	v_add_f32_e32 v122, v77, v122
	v_add_f32_e32 v123, v93, v123
	v_add_u32_e32 v124, s12, v225
	ds_read_b64_tr_b16 v[110:111], v227 offset:13824
	ds_read_b64_tr_b16 v[112:113], v227 offset:15872
	ds_read_b128 v[166:169], v124
	ds_read_b128 v[162:165], v124 offset:8192
	s_waitcnt lgkmcnt(8)
	v_mfma_f32_32x32x16_bf16 v[34:49], v[114:117], v[106:109], v[34:49]
	v_exp_f32_e32 v95, v95
	v_exp_f32_e32 v79, v79
	v_add_f32_e32 v106, v78, v122
	v_add_f32_e32 v107, v94, v123
	s_waitcnt lgkmcnt(6)
	v_mfma_f32_32x32x16_bf16 v[18:33], v[114:117], v[118:121], v[18:33]
	v_exp_f32_e32 v96, v96
	v_exp_f32_e32 v80, v80
	v_add_f32_e32 v106, v79, v106
	v_add_f32_e32 v107, v95, v107
	s_waitcnt lgkmcnt(2)
	v_mfma_f32_32x32x16_bf16 v[2:17], v[114:117], v[110:113], v[2:17]
	v_exp_f32_e32 v97, v97
	v_exp_f32_e32 v81, v81
	v_add_f32_e32 v106, v80, v106
	v_add_f32_e32 v107, v96, v107
	s_nop 0
	v_add_f32_e32 v107, v97, v107
	v_add_f32_e32 v106, v81, v106
	v_add_f32_e32 v106, v107, v106
	v_mov_b32_e32 v107, v106
	s_nop 1
	v_permlane32_swap_b32_e32 v106, v107
	s_mov_b64 s[12:13], -1
	s_and_b64 vcc, exec, s[10:11]
	s_cbranch_vccz .LBB0_416
	s_waitcnt vmcnt(0) lgkmcnt(0)
	s_barrier
	s_mov_b64 s[12:13], 0

; #define SBAR() __builtin_amdgcn_sched_barrier(0)
; #define PIN(x) asm volatile("" : "+v"(x))
; template <int DK, bool NOMAX> ...
;     ...
;   float psa = 0.f, psb = 0.f;
;   SBAR();
; #pragma unroll
;   for (int d0 = 0; d0 < NS; ++d0) {
;     if (d0 == 0) { c0 = __builtin_amdgcn_mfma_f32_32x32x16_bf16(kf[0][0], qr[0], f32x16{}, 0, 0, 0); c1 = __builtin_amdgcn_mfma_f32_32x32x16_bf16(kf[0][1], qr[0], f32x16{}, 0, 0, 0); }
;     else { c0 = __builtin_amdgcn_mfma_f32_32x32x16_bf16(kf[d0 & 1][0], qr[d0], c0, 0, 0, 0); c1 = __builtin_amdgcn_mfma_f32_32x32x16_bf16(kf[d0 & 1][1], qr[d0], c1, 0, 0, 0); }
;     if (d0 + 2 < NS) KRD_(d0 & 1, d0 + 2);
;     if constexpr (NOMAX) { }
;     else {
; #pragma unroll
;     for (int r = d0 * RPS; r < (d0 + 1) * RPS; ++r) { p1[r] = __builtin_amdgcn_exp2f(p1[r]); psa += p0[r]; }
;     if (d0 > 0) {
; #pragma unroll
;       for (int r = (d0 - 1) * RPS; r < d0 * RPS; ++r) psb += p1[r]; } }
;     if constexpr (NOMAX) {
;       if (d0 == NS / 4 - 1) { PK4R(p0, 0, pa[0]); PIN(pa[0]); }
;       if (d0 == NS / 2 - 1) { PK4R(p0, 8, pa[1]); PIN(pa[1]); }
;       if (d0 == 3 * NS / 4 - 1) { PK4R(p1, 0, pa[2]); PIN(pa[2]); }
;       if (d0 == NS - 1) { PK4R(p1, 8, pa[3]); PIN(pa[3]); }
;     } else {
;     if (d0 == NS / 2 - 1) { PK4R(p0, 0, pa[0]); PIN(pa[0]); }
;     if (d0 == NS / 2) { PK4R(p0, 8, pa[1]); PIN(pa[1]); }
;     if (d0 == NS - 1) { PK4R(p1, 0, pa[2]); PIN(pa[2]); }
;     }
;     if (d0 == NS - 1) {
;       vl[0] = vtr(vp + v_rd_off(0, 0, 0)); vh[0] = vtr(vp + v_rd_off(0, 0, 1)); vl[1] = vtr(vp + v_rd_off(1, 0, 0)); vh[1] = vtr(vp + v_rd_off(1, 0, 1)); }
;     PIN(p1); PIN(psa); PIN(psb);
;     SBAR();
;   }
; template <int DK, bool NOMAX> ...
;     ...
; #pragma unroll
;   for (int i = 0; i < 16; ++i) {
;     if (i + 2 < 16) VRD_((i + 2) % 3, i + 2);
;     if (i == 1) { if (dk) __builtin_amdgcn_global_load_lds((const unsigned*)gk0, lk, 16, 0, 0); }
;     if (i == 3) { if constexpr (DK == 128) { if (dk) __builtin_amdgcn_global_load_lds((const unsigned*)gk1, (lds_up)((lds_cp)lk + 8192), 16, 0, 0); } }
;     if (i == 5) { if (dv) __builtin_amdgcn_global_load_lds((const unsigned*)gv0, lv, 16, 0, 0); }
;     if (i == 7) { if (dv) __builtin_amdgcn_global_load_lds((const unsigned*)gv1, (lds_up)((lds_cp)lv + 8192), 16, 0, 0); }
;     if (i == 12 || i == 13) { const int cb_ = ((i - 12) * 16 + hi * 8) * 2;
.LBB0_462:
	s_mov_b32 s17, s15
	s_mov_b32 s15, s8
	s_add_i32 s8, s18, 0xffffc000
	s_and_b32 s38, s8, 0xc000
	s_add_i32 s8, s38, 0
	v_add_u32_e32 v0, s15, v204
	s_waitcnt lgkmcnt(0)
	v_mfma_f32_32x32x16_bf16 v[114:129], v[102:105], v[158:161], 0
	v_add_u32_e32 v188, s8, v218
	ds_read_b128 v[184:187], v188
	ds_read_b128 v[188:191], v188 offset:8192
	v_mfma_f32_32x32x16_bf16 v[98:113], v[98:101], v[158:161], 0
	v_mfma_f32_32x32x16_bf16 v[114:129], v[166:169], v[154:157], v[114:129]
	v_mfma_f32_32x32x16_bf16 v[98:113], v[162:165], v[154:157], v[98:113]
	v_add_u32_e32 v162, s8, v219
	ds_read_b128 v[166:169], v162
	ds_read_b128 v[226:229], v162 offset:8192
	v_cvt_pk_bf16_f32 v162, v82, v83
	v_cvt_pk_bf16_f32 v163, v84, v85
	v_cvt_pk_bf16_f32 v164, v86, v87
	v_cvt_pk_bf16_f32 v165, v88, v89
	s_nop 0
	v_permlane32_swap_b32_e32 v162, v164
	v_permlane32_swap_b32_e32 v163, v165
	s_waitcnt lgkmcnt(3)
	v_mfma_f32_32x32x16_bf16 v[114:129], v[184:187], v[150:153], v[114:129]
	v_add_u32_e32 v86, s8, v220
	ds_read_b128 v[82:85], v86
	ds_read_b128 v[86:89], v86 offset:8192
	s_waitcnt lgkmcnt(4)
	v_mfma_f32_32x32x16_bf16 v[98:113], v[188:191], v[150:153], v[98:113]
	s_waitcnt lgkmcnt(3)
	v_mfma_f32_32x32x16_bf16 v[114:129], v[166:169], v[146:149], v[114:129]
	v_add_u32_e32 v184, s8, v221
	ds_read_b128 v[166:169], v184
	ds_read_b128 v[184:187], v184 offset:8192
	v_cvt_pk_bf16_f32 v90, v90, v91
	v_cvt_pk_bf16_f32 v91, v92, v93
	v_cvt_pk_bf16_f32 v92, v94, v95
	v_cvt_pk_bf16_f32 v93, v96, v97
	s_waitcnt lgkmcnt(4)
	v_mfma_f32_32x32x16_bf16 v[98:113], v[226:229], v[146:149], v[98:113]
	v_permlane32_swap_b32_e32 v90, v92
	v_permlane32_swap_b32_e32 v91, v93
	s_waitcnt lgkmcnt(3)
	v_mfma_f32_32x32x16_bf16 v[114:129], v[82:85], v[142:145], v[114:129]
	s_waitcnt lgkmcnt(2)
	v_mfma_f32_32x32x16_bf16 v[98:113], v[86:89], v[142:145], v[98:113]
	v_add_u32_e32 v86, s8, v222
	ds_read_b128 v[82:85], v86
	ds_read_b128 v[94:97], v86 offset:8192
	s_waitcnt lgkmcnt(3)
	v_mfma_f32_32x32x16_bf16 v[114:129], v[166:169], v[138:141], v[114:129]
	v_add_u32_e32 v86, s8, v223
	s_waitcnt lgkmcnt(2)
	v_mfma_f32_32x32x16_bf16 v[98:113], v[184:187], v[138:141], v[98:113]
	ds_read_b128 v[166:169], v86
	ds_read_b128 v[184:187], v86 offset:8192
	v_cvt_pk_bf16_f32 v86, v66, v67
	v_cvt_pk_bf16_f32 v87, v68, v69
	v_cvt_pk_bf16_f32 v88, v70, v71
	v_cvt_pk_bf16_f32 v89, v72, v73
	s_nop 0
	v_permlane32_swap_b32_e32 v86, v88
	v_permlane32_swap_b32_e32 v87, v89
	s_waitcnt lgkmcnt(3)
	v_mfma_f32_32x32x16_bf16 v[114:129], v[82:85], v[130:133], v[114:129]
	s_waitcnt lgkmcnt(2)
	v_mfma_f32_32x32x16_bf16 v[98:113], v[94:97], v[130:133], v[98:113]
	v_cvt_pk_bf16_f32 v82, v74, v75
	v_cvt_pk_bf16_f32 v83, v76, v77
	v_cvt_pk_bf16_f32 v84, v78, v79
	v_cvt_pk_bf16_f32 v85, v80, v81
	s_waitcnt lgkmcnt(1)
	v_mfma_f32_32x32x16_bf16 v[114:129], v[166:169], v[134:137], v[114:129]
	v_permlane32_swap_b32_e32 v82, v84
	v_permlane32_swap_b32_e32 v83, v85
	ds_read_b64_tr_b16 v[166:167], v0
	ds_read_b64_tr_b16 v[168:169], v0 offset:2048
	ds_read_b64_tr_b16 v[94:95], v0 offset:512
	ds_read_b64_tr_b16 v[96:97], v0 offset:2560
	s_waitcnt lgkmcnt(4)
	v_mfma_f32_32x32x16_bf16 v[98:113], v[184:187], v[134:137], v[98:113]
	s_cmp_lt_u32 s14, 61
	s_cselect_b64 s[10:11], -1, 0
	s_cmp_gt_u32 s14, 60
	s_cselect_b64 s[8:9], -1, 0
	s_add_i32 s19, s18, 0x8000
	s_and_b32 s12, s19, 0xc000
	ds_read_b64_tr_b16 v[70:71], v0 offset:1024
	ds_read_b64_tr_b16 v[72:73], v0 offset:3072
	s_waitcnt lgkmcnt(4)
	v_mfma_f32_32x32x16_bf16 v[50:65], v[162:165], v[166:169], v[50:65]
	v_exp_f32_e32 v114, v114
	s_nop 0
	v_exp_f32_e32 v98, v98
	ds_read_b64_tr_b16 v[66:67], v0 offset:1536
	ds_read_b64_tr_b16 v[68:69], v0 offset:3584
	s_and_b64 vcc, exec, s[8:9]
	s_cbranch_vccnz .LBB0_464
	s_add_u32 vcc_lo, s0, s50
	s_addc_u32 vcc_hi, s1, s51
	s_add_i32 m0, s2, s12
	s_nop 0
	global_load_lds_dwordx4 v182, vcc

; #define SBAR() __builtin_amdgcn_sched_barrier(0)
; #define PIN(x) asm volatile("" : "+v"(x))
; template <int DK, bool NOMAX> ...
;     ...
;   float psa = 0.f, psb = 0.f;
;   SBAR();
; #pragma unroll
;   for (int d0 = 0; d0 < NS; ++d0) {
;     if (d0 == 0) { c0 = __builtin_amdgcn_mfma_f32_32x32x16_bf16(kf[0][0], qr[0], f32x16{}, 0, 0, 0); c1 = __builtin_amdgcn_mfma_f32_32x32x16_bf16(kf[0][1], qr[0], f32x16{}, 0, 0, 0); }
;     else { c0 = __builtin_amdgcn_mfma_f32_32x32x16_bf16(kf[d0 & 1][0], qr[d0], c0, 0, 0, 0); c1 = __builtin_amdgcn_mfma_f32_32x32x16_bf16(kf[d0 & 1][1], qr[d0], c1, 0, 0, 0); }
;     if (d0 + 2 < NS) KRD_(d0 & 1, d0 + 2);
;     if constexpr (NOMAX) { }
;     else {
; #pragma unroll
;     for (int r = d0 * RPS; r < (d0 + 1) * RPS; ++r) { p1[r] = __builtin_amdgcn_exp2f(p1[r]); psa += p0[r]; }
;     if (d0 > 0) {
; #pragma unroll
;       for (int r = (d0 - 1) * RPS; r < d0 * RPS; ++r) psb += p1[r]; } }
;     if constexpr (NOMAX) {
;       if (d0 == NS / 4 - 1) { PK4R(p0, 0, pa[0]); PIN(pa[0]); }
;       if (d0 == NS / 2 - 1) { PK4R(p0, 8, pa[1]); PIN(pa[1]); }
;       if (d0 == 3 * NS / 4 - 1) { PK4R(p1, 0, pa[2]); PIN(pa[2]); }
;       if (d0 == NS - 1) { PK4R(p1, 8, pa[3]); PIN(pa[3]); }
;     } else {
;     if (d0 == NS / 2 - 1) { PK4R(p0, 0, pa[0]); PIN(pa[0]); }
;     if (d0 == NS / 2) { PK4R(p0, 8, pa[1]); PIN(pa[1]); }
;     if (d0 == NS - 1) { PK4R(p1, 0, pa[2]); PIN(pa[2]); }
;     }
;     if (d0 == NS - 1) {
;       vl[0] = vtr(vp + v_rd_off(0, 0, 0)); vh[0] = vtr(vp + v_rd_off(0, 0, 1)); vl[1] = vtr(vp + v_rd_off(1, 0, 0)); vh[1] = vtr(vp + v_rd_off(1, 0, 1)); }
;     PIN(p1); PIN(psa); PIN(psb);
;     SBAR();
;   }
; template <int DK, bool NOMAX> ...
;     ...
; #pragma unroll
;   for (int i = 0; i < 16; ++i) {
;     if (i + 2 < 16) VRD_((i + 2) % 3, i + 2);
;     if (i == 1) { if (dk) __builtin_amdgcn_global_load_lds((const unsigned*)gk0, lk, 16, 0, 0); }
;     if (i == 3) { if constexpr (DK == 128) { if (dk) __builtin_amdgcn_global_load_lds((const unsigned*)gk1, (lds_up)((lds_cp)lk + 8192), 16, 0, 0); } }
;     if (i == 5) { if (dv) __builtin_amdgcn_global_load_lds((const unsigned*)gv0, lv, 16, 0, 0); }
;     if (i == 7) { if (dv) __builtin_amdgcn_global_load_lds((const unsigned*)gv1, (lds_up)((lds_cp)lv + 8192), 16, 0, 0); }
;     if (i == 12 || i == 13) { const int cb_ = ((i - 12) * 16 + hi * 8) * 2;
.LBB0_470:
	v_add_u32_e32 v227, s17, v204
	v_mfma_f32_32x32x16_bf16 v[82:97], v[66:69], v[158:161], 0
	v_add_u32_e32 v232, s12, v218
	ds_read_b128 v[228:231], v232
	ds_read_b128 v[232:235], v232 offset:8192
	v_mfma_f32_32x32x16_bf16 v[66:81], v[70:73], v[158:161], 0
	v_mfma_f32_32x32x16_bf16 v[82:97], v[162:165], v[154:157], v[82:97]
	v_add_u32_e32 v162, s12, v219
	v_mfma_f32_32x32x16_bf16 v[66:81], v[166:169], v[154:157], v[66:81]
	ds_read_b128 v[166:169], v162
	ds_read_b128 v[236:239], v162 offset:8192
	v_cvt_pk_bf16_f32 v162, v114, v115
	v_cvt_pk_bf16_f32 v163, v116, v117
	v_cvt_pk_bf16_f32 v164, v118, v119
	v_cvt_pk_bf16_f32 v165, v120, v121
	s_nop 0
	v_permlane32_swap_b32_e32 v162, v164
	v_permlane32_swap_b32_e32 v163, v165
	s_waitcnt lgkmcnt(3)
	v_mfma_f32_32x32x16_bf16 v[82:97], v[228:231], v[150:153], v[82:97]
	v_add_u32_e32 v118, s12, v220
	ds_read_b128 v[114:117], v118
	ds_read_b128 v[118:121], v118 offset:8192
	s_waitcnt lgkmcnt(4)
	v_mfma_f32_32x32x16_bf16 v[66:81], v[232:235], v[150:153], v[66:81]
	s_waitcnt lgkmcnt(3)
	v_mfma_f32_32x32x16_bf16 v[82:97], v[166:169], v[146:149], v[82:97]
	v_add_u32_e32 v228, s12, v221
	ds_read_b128 v[166:169], v228
	ds_read_b128 v[228:231], v228 offset:8192
	v_cvt_pk_bf16_f32 v122, v122, v123
	v_cvt_pk_bf16_f32 v123, v124, v125
	v_cvt_pk_bf16_f32 v124, v126, v127
	v_cvt_pk_bf16_f32 v125, v128, v129
	s_waitcnt lgkmcnt(4)
	v_mfma_f32_32x32x16_bf16 v[66:81], v[236:239], v[146:149], v[66:81]
	v_permlane32_swap_b32_e32 v122, v124
	v_permlane32_swap_b32_e32 v123, v125
	s_waitcnt lgkmcnt(3)
	v_mfma_f32_32x32x16_bf16 v[82:97], v[114:117], v[142:145], v[82:97]
	s_waitcnt lgkmcnt(2)
	v_mfma_f32_32x32x16_bf16 v[66:81], v[118:121], v[142:145], v[66:81]
	v_add_u32_e32 v118, s12, v222
	ds_read_b128 v[114:117], v118
	ds_read_b128 v[126:129], v118 offset:8192
	s_waitcnt lgkmcnt(3)
	v_mfma_f32_32x32x16_bf16 v[82:97], v[166:169], v[138:141], v[82:97]
	v_add_u32_e32 v118, s12, v223
	s_waitcnt lgkmcnt(2)
	v_mfma_f32_32x32x16_bf16 v[66:81], v[228:231], v[138:141], v[66:81]
	ds_read_b128 v[166:169], v118
	ds_read_b128 v[228:231], v118 offset:8192
	v_cvt_pk_bf16_f32 v118, v98, v99
	v_cvt_pk_bf16_f32 v119, v100, v101
	v_cvt_pk_bf16_f32 v120, v102, v103
	v_cvt_pk_bf16_f32 v121, v104, v105
	s_nop 0
	v_permlane32_swap_b32_e32 v118, v120
	v_permlane32_swap_b32_e32 v119, v121
	s_waitcnt lgkmcnt(3)
	v_mfma_f32_32x32x16_bf16 v[82:97], v[114:117], v[130:133], v[82:97]
	s_waitcnt lgkmcnt(2)
	v_mfma_f32_32x32x16_bf16 v[66:81], v[126:129], v[130:133], v[66:81]
	v_cvt_pk_bf16_f32 v114, v106, v107
	v_cvt_pk_bf16_f32 v115, v108, v109
	v_cvt_pk_bf16_f32 v116, v110, v111
	v_cvt_pk_bf16_f32 v117, v112, v113
	s_waitcnt lgkmcnt(1)
	v_mfma_f32_32x32x16_bf16 v[82:97], v[166:169], v[134:137], v[82:97]
	v_permlane32_swap_b32_e32 v114, v116
	v_permlane32_swap_b32_e32 v115, v117
	ds_read_b64_tr_b16 v[166:167], v227
	ds_read_b64_tr_b16 v[168:169], v227 offset:2048
	ds_read_b64_tr_b16 v[126:127], v227 offset:512
	ds_read_b64_tr_b16 v[128:129], v227 offset:2560
	s_waitcnt lgkmcnt(4)
	v_mfma_f32_32x32x16_bf16 v[66:81], v[228:231], v[134:137], v[66:81]
	s_cmp_lt_u32 s14, 60
	s_cselect_b64 s[12:13], -1, 0
	s_cmp_gt_u32 s14, 59
	s_cselect_b64 s[10:11], -1, 0
	ds_read_b64_tr_b16 v[102:103], v227 offset:1024
	ds_read_b64_tr_b16 v[104:105], v227 offset:3072
	s_waitcnt lgkmcnt(4)
	v_mfma_f32_32x32x16_bf16 v[50:65], v[162:165], v[166:169], v[50:65]
	v_exp_f32_e32 v82, v82
	s_nop 2
	v_exp_f32_e32 v66, v66
	ds_read_b64_tr_b16 v[98:99], v227 offset:1536
	ds_read_b64_tr_b16 v[100:101], v227 offset:3584
	s_and_b64 vcc, exec, s[10:11]
	s_cbranch_vccnz .LBB0_472
	s_add_u32 vcc_lo, s0, s64
	s_addc_u32 vcc_hi, s1, s65
	s_add_i32 m0, s2, s38
	s_nop 0
	global_load_lds_dwordx4 v182, vcc

; #define SBAR() __builtin_amdgcn_sched_barrier(0)
; #define PIN(x) asm volatile("" : "+v"(x))
; #define VRD_(S, I) do { vl[S] = vtr(vp + v_rd_off((I) & 3, (I) >> 2, 0)); vh[S] = vtr(vp + v_rd_off((I) & 3, (I) >> 2, 1)); } while (0)
; template <int DK, bool NOMAX> ...
;     ...
;   for (int i = 0; i < 16; ++i) {
;     if (i + 2 < 16) VRD_((i + 2) % 3, i + 2);
;     if (i == 1) { if (dk) __builtin_amdgcn_global_load_lds((const unsigned*)gk0, lk, 16, 0, 0); }
;     if (i == 3) { if constexpr (DK == 128) { if (dk) __builtin_amdgcn_global_load_lds((const unsigned*)gk1, (lds_up)((lds_cp)lk + 8192), 16, 0, 0); } }
;     if (i == 5) { if (dv) __builtin_amdgcn_global_load_lds((const unsigned*)gv0, lv, 16, 0, 0); }
;     if (i == 7) { if (dv) __builtin_amdgcn_global_load_lds((const unsigned*)gv1, (lds_up)((lds_cp)lv + 8192), 16, 0, 0); }
;     if (i == 12 || i == 13) { const int cb_ = ((i - 12) * 16 + hi * 8) * 2;
;       if constexpr (DK == 128) { kf[i - 12][0] = *reinterpret_cast<const bf16x8*>(Kn + KSWZ128(r32, cb_)); kf[i - 12][1] = *reinterpret_cast<const bf16x8*>(Kn + KSWZ128(32 + r32, cb_)); }
;       else { kf[i - 12][0] = *reinterpret_cast<const bf16x8*>(Kn + KSWZ64(r32, cb_)); kf[i - 12][1] = *reinterpret_cast<const bf16x8*>(Kn + KSWZ64(32 + r32, cb_)); } }
;     SBAR();
;     o[i & 3] = __builtin_amdgcn_mfma_f32_32x32x16_bf16(pa[i >> 2], VFR_(i % 3), o[i & 3], 0, 0, 0);
;     if constexpr (NOMAX) { c0[i] = __builtin_amdgcn_exp2f(c0[i]); c1[i] = __builtin_amdgcn_exp2f(c1[i]); if (i > 0) { psa += c0[i - 1]; psb += c1[i - 1]; } PIN(c0); PIN(c1); PIN(psa); PIN(psb); }
.LBB0_474:
	s_add_i32 s12, s18, 0x4000
	s_and_b32 s12, s12, 0xc000
	s_add_i32 s12, s12, 0
	s_waitcnt lgkmcnt(4)
	v_mfma_f32_32x32x16_bf16 v[2:17], v[162:165], v[98:101], v[2:17]
	v_exp_f32_e32 v85, v85
	v_exp_f32_e32 v69, v69
	v_add_f32_e32 v111, v68, v111
	v_add_f32_e32 v110, v84, v110
	ds_read_b64_tr_b16 v[98:99], v227 offset:5120
	ds_read_b64_tr_b16 v[100:101], v227 offset:7168
	s_waitcnt lgkmcnt(4)
	v_mfma_f32_32x32x16_bf16 v[50:65], v[122:125], v[106:109], v[50:65]
	v_exp_f32_e32 v86, v86
	v_exp_f32_e32 v70, v70
	v_add_f32_e32 v111, v69, v111
	v_add_f32_e32 v110, v85, v110
	s_add_u32 vcc_lo, s0, s24
	s_addc_u32 vcc_hi, s1, s25
	s_add_i32 s13, s3, s15
	s_mov_b32 m0, s13
	ds_read_b64_tr_b16 v[106:107], v227 offset:5632
	ds_read_b64_tr_b16 v[108:109], v227 offset:7680
	global_load_lds_dwordx4 v172, vcc
	s_waitcnt lgkmcnt(4)
	v_mfma_f32_32x32x16_bf16 v[34:49], v[122:125], v[102:105], v[34:49]
	v_exp_f32_e32 v87, v87
	v_exp_f32_e32 v71, v71
	v_add_f32_e32 v111, v70, v111
	v_add_f32_e32 v110, v86, v110
	ds_read_b64_tr_b16 v[102:103], v227 offset:8192
	ds_read_b64_tr_b16 v[104:105], v227 offset:10240
	s_waitcnt lgkmcnt(4)
	v_mfma_f32_32x32x16_bf16 v[18:33], v[122:125], v[98:101], v[18:33]
	v_exp_f32_e32 v88, v88
	v_exp_f32_e32 v72, v72
	v_add_f32_e32 v111, v71, v111
	v_add_f32_e32 v110, v87, v110
	s_add_i32 m0, s13, 0x2000
	ds_read_b64_tr_b16 v[98:99], v227 offset:8704
	ds_read_b64_tr_b16 v[100:101], v227 offset:10752
	global_load_lds_dwordx4 v170, vcc
	s_waitcnt lgkmcnt(4)
	v_mfma_f32_32x32x16_bf16 v[2:17], v[122:125], v[106:109], v[2:17]
	v_exp_f32_e32 v89, v89
	v_exp_f32_e32 v73, v73
	v_add_f32_e32 v111, v72, v111
	v_add_f32_e32 v110, v88, v110
	ds_read_b64_tr_b16 v[106:107], v227 offset:9216
	ds_read_b64_tr_b16 v[108:109], v227 offset:11264
	s_waitcnt lgkmcnt(4)
	v_mfma_f32_32x32x16_bf16 v[50:65], v[118:121], v[102:105], v[50:65]
	v_exp_f32_e32 v90, v90
	v_exp_f32_e32 v74, v74
	v_add_f32_e32 v111, v73, v111
	v_add_f32_e32 v110, v89, v110
	ds_read_b64_tr_b16 v[102:103], v227 offset:9728
	ds_read_b64_tr_b16 v[104:105], v227 offset:11776
	s_waitcnt lgkmcnt(4)
	v_mfma_f32_32x32x16_bf16 v[34:49], v[118:121], v[98:101], v[34:49]
	v_exp_f32_e32 v91, v91
	v_exp_f32_e32 v75, v75
	v_add_f32_e32 v98, v74, v111
	v_add_f32_e32 v99, v90, v110
	ds_read_b64_tr_b16 v[110:111], v227 offset:12288
	ds_read_b64_tr_b16 v[112:113], v227 offset:14336
	s_waitcnt lgkmcnt(4)
	v_mfma_f32_32x32x16_bf16 v[18:33], v[118:121], v[106:109], v[18:33]
	v_exp_f32_e32 v92, v92
	v_exp_f32_e32 v76, v76
	v_add_f32_e32 v98, v75, v98
	v_add_f32_e32 v99, v91, v99
	ds_read_b64_tr_b16 v[106:107], v227 offset:12800
	ds_read_b64_tr_b16 v[108:109], v227 offset:14848
	s_waitcnt lgkmcnt(4)
	v_mfma_f32_32x32x16_bf16 v[2:17], v[118:121], v[102:105], v[2:17]
	v_exp_f32_e32 v93, v93
	v_exp_f32_e32 v77, v77
	v_add_f32_e32 v122, v76, v98
	v_add_f32_e32 v123, v92, v99
	v_add_u32_e32 v98, s12, v224
	ds_read_b64_tr_b16 v[118:119], v227 offset:13312
	ds_read_b64_tr_b16 v[120:121], v227 offset:15360
	ds_read_b128 v[102:105], v98
	ds_read_b128 v[98:101], v98 offset:8192
	s_waitcnt lgkmcnt(6)
	v_mfma_f32_32x32x16_bf16 v[50:65], v[114:117], v[110:113], v[50:65]
	v_exp_f32_e32 v94, v94
	v_exp_f32_e32 v78, v78
	v_add_f32_e32 v122, v77, v122
	v_add_f32_e32 v123, v93, v123
	v_add_u32_e32 v124, s12, v225
	ds_read_b64_tr_b16 v[110:111], v227 offset:13824
	ds_read_b64_tr_b16 v[112:113], v227 offset:15872
	ds_read_b128 v[166:169], v124
	ds_read_b128 v[162:165], v124 offset:8192
	s_waitcnt lgkmcnt(8)
	v_mfma_f32_32x32x16_bf16 v[34:49], v[114:117], v[106:109], v[34:49]
	v_exp_f32_e32 v95, v95
	v_exp_f32_e32 v79, v79
	v_add_f32_e32 v106, v78, v122
	v_add_f32_e32 v107, v94, v123
	s_waitcnt lgkmcnt(6)
	v_mfma_f32_32x32x16_bf16 v[18:33], v[114:117], v[118:121], v[18:33]
	v_exp_f32_e32 v96, v96
	v_exp_f32_e32 v80, v80
	v_add_f32_e32 v106, v79, v106
	v_add_f32_e32 v107, v95, v107
	s_waitcnt lgkmcnt(2)
	v_mfma_f32_32x32x16_bf16 v[2:17], v[114:117], v[110:113], v[2:17]
	v_exp_f32_e32 v97, v97
	v_exp_f32_e32 v81, v81
	v_add_f32_e32 v106, v80, v106
	v_add_f32_e32 v107, v96, v107
	s_nop 0
	v_add_f32_e32 v107, v97, v107
	v_add_f32_e32 v106, v81, v106
	v_add_f32_e32 v106, v107, v106
	v_mov_b32_e32 v107, v106
	s_nop 1
	v_permlane32_swap_b32_e32 v106, v107
	s_mov_b64 s[12:13], -1
	s_and_b64 vcc, exec, s[10:11]
	s_cbranch_vccz .LBB0_476
	s_waitcnt vmcnt(0) lgkmcnt(0)
	s_barrier
	s_mov_b64 s[12:13], 0
